# ffn_up epilogue: RMSNorm row factors cached in LDS across a workgroup's tiles that share the row block (same values, computed once per row block)
# speedup vs baseline: 1.0253x; 1.0150x over previous
; #define PG8_WAIT_V(n) asm volatile("s_waitcnt vmcnt(" #n ")" ::: "memory")
; #define PG8_BAR __builtin_amdgcn_s_barrier()
; template <class Epi, class Sched, bool ALIGN_EPI = false, bool SP2 = false>
; __device__ __forceinline__ void gemm_phase(PG8_LAS unsigned char* lds, const Gemm g, const Sched& S, const Epi& E) {
;     int tid_ = threadIdx.x; asm volatile("" : "+v"(tid_));
;     const int tid = tid_, wid = __builtin_amdgcn_readfirstlane(tid >> 6), lane = tid & 63, wr = wid >> 2, wc = wid & 3, fr = lane & 15, fq = lane >> 4;
;     const int K = g.K, nt = K / BK;
;     unsigned voffA[2], voffB[2];
; #pragma unroll
;     for (int i = 0; i < 2; ++i) { int R, C; stage_rc(tid * 16 + i * 8192, R, C); const int Rb = Epi::PERM ? ((R & ~31) + perm32(R & 31)) : R;
;         voffA[i] = (unsigned)(R * K + C) * 2u; voffB[i] = (unsigned)(Rb * K + C) * 2u; }
;     const size_t kstep = (size_t)(BK * 2);
;     const size_t hstep = (size_t)HALF * K * 2;
;     const size_t tstep = 2 * hstep;
;     const unsigned ldsw = (unsigned)wid * 1024u;
;     const int aoff = lds_byte(wr * 64 + fr, fq * 8), boff = lds_byte(wc * 32 + fr, fq * 8);
;     ...
;     Unit cur, nxt; int ui = 0;
;     if (!S.next(0, cur)) return;
;     f32x4 acc[2][2][4][2];
; #pragma unroll
;     for (int a = 0; a < 2; ++a)
; #pragma unroll
;         for (int b = 0; b < 2; ++b)
; #pragma unroll
;             for (int m = 0; m < 4; ++m)
; #pragma unroll
;                 for (int n = 0; n < 2; ++n) acc[a][b][m][n] = (f32x4){0.f, 0.f, 0.f, 0.f};
;     bf16x8 At[4][2], B0[2][2], B1[2][2];
;     const char* cA = (const char*)g.A + (size_t)cur.pm * tstep; const char* cB = (const char*)g.Bt + (size_t)cur.pn * tstep;
;     S.a_ready(cur);
;     if constexpr (SP2) {
;         PG8_STAGE(PG8_SB(0, 0), cB, voffB); PG8_STAGE(PG8_SB(0, 1), cB + hstep, voffB); PG8_STAGE(PG8_SA(0, 0), cA, voffA); PG8_STAGE(PG8_SA(0, 1), cA + hstep, voffA);
;         if (wr == 1) PG8_BAR;
;         PG8_WAIT_V(2); PG8_BAR;
;         PG8_STAGE(PG8_SB(1, 0), cB + kstep, voffB); PG8_STAGE(PG8_SA(1, 0), cA + kstep, voffA); PG8_STAGE(PG8_SB(1, 1), cB + hstep + kstep, voffB);
;         PG8_WAIT_V(6); PG8_BAR;
;     } else {
;         PG8_STAGE(PG8_SB(0, 0), cB, voffB); PG8_STAGE(PG8_SA(0, 0), cA, voffA); PG8_STAGE(PG8_SB(0, 1), cB + hstep, voffB); PG8_STAGE(PG8_SA(0, 1), cA + hstep, voffA);
;         if (wr == 1) PG8_BAR;
;         PG8_WAIT_V(4); PG8_BAR;
.LBB0_1879:
	s_add_u32 s14, s6, 0x2ea00000
	v_readlane_b32 s9, v255, 4
	s_addc_u32 s15, s7, 0
	s_mul_i32 s9, s9, 0x21000
	s_add_u32 s40, s4, s9
	v_lshrrev_b32_e32 v15, 1, v12
	s_addc_u32 s41, s5, 0
	v_and_b32_e32 v15, 24, v15
	s_add_u32 s16, s6, 0x47800000
	v_and_b32_e32 v178, 15, v12
	v_lshlrev_b32_e32 v16, 1, v15
	v_lshlrev_b32_e32 v12, 2, v12
	s_addc_u32 s17, s7, 0
	v_lshl_or_b32 v16, v178, 6, v16
	s_lshl_b32 s4, s34, 13
	v_and_b32_e32 v12, 32, v12
	v_bitop3_b32 v17, v16, s4, v12 bitop3:0xde
	s_lshl_b32 s4, s18, 5
	s_add_i32 s92, s37, 0x18000
	s_and_b32 s9, s4, 0x60
	s_add_i32 s93, s92, s1
	s_add_i32 s91, s37, 0x20000
	s_lshl_b32 s4, s9, 7
	v_lshl_add_u64 v[4:5], v[4:5], 0, s[66:67]
	s_mov_b32 m0, s93
	s_add_i32 s94, s93, 0x2000
	s_add_i32 s95, s82, 0x8000
	s_add_i32 s96, s82, 0xa000
	v_bitop3_b32 v236, v16, s4, v12 bitop3:0xde
	s_waitcnt vmcnt(2)
	s_barrier
	global_load_lds_dwordx4 v[4:5], off
	v_lshl_add_u64 v[2:3], v[2:3], 0, s[66:67]
	s_mov_b32 m0, s94
	s_add_u32 s4, s76, 0x80080
	global_load_lds_dwordx4 v[2:3], off
	v_lshl_add_u64 v[0:1], v[0:1], 0, s[66:67]
	s_mov_b32 m0, s95
	s_addc_u32 s5, s77, 0
	s_add_i32 s97, s37, 0x1c000
	global_load_lds_dwordx4 v[0:1], off
	v_lshl_add_u64 v[0:1], v[6:7], 0, s[66:67]
	s_mov_b32 m0, s96
	s_add_i32 s33, s97, s1
	global_load_lds_dwordx4 v[0:1], off
	v_lshl_add_u64 v[0:1], s[4:5], 0, v[172:173]
	s_mov_b32 m0, s33
	s_add_i32 s1, s33, 0x2000
	global_load_lds_dwordx4 v[0:1], off
	v_lshl_add_u64 v[0:1], s[4:5], 0, v[176:177]
	s_mov_b32 m0, s1
	s_cmpk_lt_u32 s0, 0x100
	global_load_lds_dwordx4 v[0:1], off
	s_cselect_b64 s[18:19], -1, 0
	v_cmp_gt_u32_e32 vcc, 2, v178
	s_cmp_lg_u32 s34, 3
	v_or_b32_e32 v180, s9, v15
	s_cselect_b64 s[20:21], -1, 0
	s_lshl_b32 s9, s34, 9
	s_and_b64 s[22:23], s[18:19], vcc
	s_add_i32 s11, s34, 2
	v_mov_b32_e32 v0, 0xfffff200
	s_cmp_lg_u32 s11, 3
	v_lshl_add_u32 v0, v178, 8, v0
	s_cselect_b64 s[24:25], -1, 0
	s_lshl_b32 s12, s11, 9
	v_add_u32_e32 v1, s9, v0
	v_add_u32_e32 v0, s12, v0
	s_cmp_eq_u32 s11, 0
	v_or_b32_e32 v1, v180, v1
	v_or_b32_e32 v0, v0, v180
	s_cselect_b64 s[26:27], -1, 0
	v_lshlrev_b32_e32 v2, 2, v1
	v_lshlrev_b32_e32 v3, 2, v0
	s_and_b64 s[26:27], s[26:27], vcc
	v_cmp_eq_u32_e32 vcc, 0, v178
	v_mov_b32_e32 v0, 0x3fffff00
	v_mov_b32_e32 v1, 0x3ffffe00
	v_cndmask_b32_e32 v0, v0, v1, vcc
	v_add_u32_e32 v1, s9, v0
	v_or_b32_e32 v4, v180, v1
	v_add_u32_e32 v0, s12, v0
	v_lshlrev_b32_e32 v237, 2, v4
	v_or_b32_e32 v4, v0, v180
	v_lshlrev_b32_e32 v238, 2, v4
	v_or_b32_e32 v4, 4, v180
	v_or_b32_e32 v1, v4, v1
	v_or_b32_e32 v0, v4, v0
	v_lshlrev_b32_e32 v128, 2, v15
	v_lshlrev_b32_e32 v250, 2, v1
	v_lshlrev_b32_e32 v251, 2, v0
	v_lshl_add_u64 v[0:1], s[6:7], 0, v[128:129]
	s_mov_b64 s[6:7], 0x40c00000
	v_lshl_add_u64 v[188:189], v[0:1], 0, s[6:7]
	v_lshlrev_b32_e32 v0, 15, v8
	v_and_b32_e32 v0, 0xffff0000, v0
	v_lshl_add_u32 v0, v9, 12, v0
	v_and_b32_e32 v1, 1, v8
	s_cmp_gt_i32 s34, 0
	v_lshl_or_b32 v0, v1, 6, v0
	s_cselect_b64 s[28:29], -1, 0
	s_lshl_b32 s13, s34, 11
	v_lshl_add_u32 v190, v10, 1, v0
	v_lshlrev_b32_e32 v0, 15, v11
	s_cmp_gt_i32 s34, -2
	v_and_b32_e32 v0, 0xffff0000, v0
	v_lshl_or_b32 v181, s34, 6, v178
	s_waitcnt vmcnt(6)
	s_cselect_b64 s[34:35], -1, 0
	s_lshl_b32 s9, s11, 11
	v_lshl_add_u32 v0, v13, 12, v0
	v_and_b32_e32 v1, 1, v11
	v_mov_b32_e32 v179, v129
	v_lshlrev_b32_e32 v184, 2, v180
	v_mov_b32_e32 v185, v129
	s_add_i32 s69, s91, s13
	s_add_i32 s36, s91, s9
	v_lshl_or_b32 v0, v1, 6, v0
	v_cmp_lt_u32_e64 s[4:5], 13, v178
	v_lshl_add_u64 v[182:183], v[178:179], 0, -12
	s_mov_b32 s0, 0
	v_lshlrev_b32_e32 v239, 2, v4
	s_ashr_i32 s51, s44, 31
	s_ashr_i32 s59, s39, 31
	v_lshl_add_u64 v[186:187], s[40:41], 0, v[184:185]
	s_add_i32 s61, s69, 0xfffffc00
	s_addk_i32 s69, 0xfe00
	s_add_i32 s56, s37, 0x20200
	s_add_i32 s80, s36, 0xfffffc00
	s_addk_i32 s36, 0xfe00
	v_mov_b32_e32 v191, v129
	v_lshl_add_u32 v192, v14, 1, v0
	v_mov_b32_e32 v193, v129
	v_add_u32_e32 v185, s37, v17
	v_add_u32_e32 v252, s91, v2
	v_add_u32_e32 v253, s91, v3
	v_writelane_b32 v255, -1, 40
	s_barrier
	s_branch .LBB0_1882

; __device__ __forceinline__ float rs_from_partials(const float* SSP, int row, int fq) {
;     const f32x4 a = *(const f32x4*)(SSP + (size_t)row * 32 + 8 * fq), b = *(const f32x4*)(SSP + (size_t)row * 32 + 8 * fq + 4);
;     float s = ((a[0] + a[1]) + (a[2] + a[3])) + ((b[0] + b[1]) + (b[2] + b[3]));
;     s += __shfl_xor(s, 16); s += __shfl_xor(s, 32);
;     return __builtin_amdgcn_rsqf(s * (1.f / 2048.f) + 1e-6f);
;     __device__ __forceinline__ void operator()(const f32x4 (&acc)[2][2][4][2], const Unit& u, int wr, int wc, int fr, int fq) const {
;         const int row0 = u.pm * BM + wr * 64 + fr, cidx = wc * 32 + 8 * fq;
;         float rs[2][4];
; #pragma unroll
;         for (int ai = 0; ai < 2; ++ai)
; #pragma unroll
;             for (int m = 0; m < 4; ++m) rs[ai][m] = rs_from_partials(SS, row0 + ai * HALF + m * 16, fq);
.LBB0_1888:
	v_and_b32_e32 v130, 64, v254
	v_xor_b32_e32 v128, 16, v254
	v_add_u32_e32 v130, 64, v130
	v_cmp_lt_i32_e32 vcc, v128, v130
	v_lshl_add_u32 v228, s10, 8, v181
	v_ashrrev_i32_e32 v229, 31, v228
	v_cndmask_b32_e32 v128, v254, v128, vcc
	v_lshlrev_b32_e32 v138, 2, v128
	v_xor_b32_e32 v128, 32, v254
	v_cmp_lt_i32_e32 vcc, v128, v130
	v_or_b32_e32 v226, 16, v228
	v_ashrrev_i32_e32 v227, 31, v226
	v_or_b32_e32 v224, 32, v228
	v_ashrrev_i32_e32 v225, 31, v224
	v_or_b32_e32 v220, 48, v228
	v_ashrrev_i32_e32 v221, 31, v220
	v_cndmask_b32_e32 v128, v254, v128, vcc
	v_lshlrev_b32_e32 v128, 2, v128
	v_add_u32_e32 v216, 0x80, v228
	v_ashrrev_i32_e32 v217, 31, v216
	v_add_u32_e32 v212, 0x90, v228
	v_ashrrev_i32_e32 v213, 31, v212
	v_add_u32_e32 v208, 0xa0, v228
	v_ashrrev_i32_e32 v209, 31, v208
	v_add_u32_e32 v200, 0xb0, v228
	v_ashrrev_i32_e32 v201, 31, v200
	s_ashr_i32 s11, s10, 31
	s_lshl_b64 s[48:49], s[10:11], 2
	v_readlane_b32 s74, v255, 40
	s_add_i32 s75, s91, 0x2000
	v_lshl_add_u32 v235, v181, 2, s75
	s_cmp_eq_u32 s74, s10
	s_cbranch_scc1 .Lrs_cached
	v_lshlrev_b64 v[140:141], 7, v[228:229]
	v_lshl_add_u64 v[140:141], v[188:189], 0, v[140:141]
	global_load_dwordx4 v[130:133], v[140:141], off offset:16
	global_load_dwordx4 v[134:137], v[140:141], off
	v_lshlrev_b64 v[140:141], 7, v[226:227]
	v_lshl_add_u64 v[140:141], v[188:189], 0, v[140:141]
	global_load_dwordx4 v[148:151], v[140:141], off offset:16
	global_load_dwordx4 v[152:155], v[140:141], off
	v_lshlrev_b64 v[140:141], 7, v[224:225]
	v_lshl_add_u64 v[140:141], v[188:189], 0, v[140:141]
	global_load_dwordx4 v[156:159], v[140:141], off offset:16
	global_load_dwordx4 v[160:163], v[140:141], off
	v_lshlrev_b64 v[140:141], 7, v[220:221]
	v_lshl_add_u64 v[140:141], v[188:189], 0, v[140:141]
	global_load_dwordx4 v[164:167], v[140:141], off offset:16
	global_load_dwordx4 v[202:205], v[140:141], off
	s_waitcnt vmcnt(6)
	v_add_f32_e32 v130, v130, v131
	v_add_f32_e32 v134, v134, v135
	v_add_f32_e32 v135, v136, v137
	v_add_f32_e32 v131, v132, v133
	v_add_f32_e32 v134, v134, v135
	v_add_f32_e32 v130, v130, v131
	v_add_f32_e32 v142, v134, v130
	s_waitcnt vmcnt(4)
	v_add_f32_e32 v148, v148, v149
	v_add_f32_e32 v152, v152, v153
	v_add_f32_e32 v153, v154, v155
	v_add_f32_e32 v149, v150, v151
	v_add_f32_e32 v152, v152, v153
	v_add_f32_e32 v148, v148, v149
	v_add_f32_e32 v214, v152, v148
	s_waitcnt vmcnt(2)
	v_add_f32_e32 v156, v156, v157
	v_add_f32_e32 v160, v160, v161
	v_add_f32_e32 v161, v162, v163
	v_add_f32_e32 v157, v158, v159
	v_add_f32_e32 v160, v160, v161
	v_add_f32_e32 v156, v156, v157
	v_add_f32_e32 v219, v160, v156
	s_waitcnt vmcnt(0)
	v_add_f32_e32 v164, v164, v165
	v_add_f32_e32 v202, v202, v203
	v_add_f32_e32 v203, v204, v205
	v_add_f32_e32 v165, v166, v167
	v_add_f32_e32 v202, v202, v203
	v_add_f32_e32 v164, v164, v165
	v_add_f32_e32 v210, v202, v164
	v_lshlrev_b64 v[140:141], 7, v[216:217]
	v_lshl_add_u64 v[140:141], v[188:189], 0, v[140:141]
	global_load_dwordx4 v[130:133], v[140:141], off offset:16
	global_load_dwordx4 v[134:137], v[140:141], off
	v_lshlrev_b64 v[140:141], 7, v[212:213]
	v_lshl_add_u64 v[140:141], v[188:189], 0, v[140:141]
	global_load_dwordx4 v[148:151], v[140:141], off offset:16
	global_load_dwordx4 v[152:155], v[140:141], off
	v_lshlrev_b64 v[140:141], 7, v[208:209]
	v_lshl_add_u64 v[140:141], v[188:189], 0, v[140:141]
	global_load_dwordx4 v[156:159], v[140:141], off offset:16
	global_load_dwordx4 v[160:163], v[140:141], off
	v_lshlrev_b64 v[140:141], 7, v[200:201]
	v_lshl_add_u64 v[140:141], v[188:189], 0, v[140:141]
	global_load_dwordx4 v[164:167], v[140:141], off offset:16
	global_load_dwordx4 v[202:205], v[140:141], off
	ds_bpermute_b32 v222, v138, v142
	ds_bpermute_b32 v223, v138, v214
	ds_bpermute_b32 v218, v138, v219
	ds_bpermute_b32 v168, v138, v210
	s_waitcnt lgkmcnt(3)
	v_add_f32_e32 v142, v142, v222
	s_waitcnt lgkmcnt(2)
	v_add_f32_e32 v214, v214, v223
	s_waitcnt lgkmcnt(1)
	v_add_f32_e32 v219, v219, v218
	s_waitcnt lgkmcnt(0)
	v_add_f32_e32 v210, v210, v168
	ds_bpermute_b32 v143, v128, v142
	ds_bpermute_b32 v215, v128, v214
	ds_bpermute_b32 v225, v128, v219
	ds_bpermute_b32 v169, v128, v210
	s_waitcnt vmcnt(6)
	v_add_f32_e32 v130, v130, v131
	v_add_f32_e32 v134, v134, v135
	v_add_f32_e32 v135, v136, v137
	v_add_f32_e32 v131, v132, v133
	v_add_f32_e32 v134, v134, v135
	v_add_f32_e32 v130, v130, v131
	v_add_f32_e32 v144, v134, v130
	s_waitcnt vmcnt(4)
	v_add_f32_e32 v148, v148, v149
	v_add_f32_e32 v152, v152, v153
	v_add_f32_e32 v153, v154, v155
	v_add_f32_e32 v149, v150, v151
	v_add_f32_e32 v152, v152, v153
	v_add_f32_e32 v148, v148, v149
	v_add_f32_e32 v199, v152, v148
	s_waitcnt vmcnt(2)
	v_add_f32_e32 v156, v156, v157
	v_add_f32_e32 v160, v160, v161
	v_add_f32_e32 v161, v162, v163
	v_add_f32_e32 v157, v158, v159
	v_add_f32_e32 v160, v160, v161
	v_add_f32_e32 v156, v156, v157
	v_add_f32_e32 v209, v160, v156
	s_waitcnt vmcnt(0)
	v_add_f32_e32 v164, v164, v165
	v_add_f32_e32 v202, v202, v203
	v_add_f32_e32 v203, v204, v205
	v_add_f32_e32 v165, v166, v167
	v_add_f32_e32 v202, v202, v203
	v_add_f32_e32 v164, v164, v165
	v_add_f32_e32 v146, v202, v164
	s_waitcnt lgkmcnt(0)
	v_add_f32_e32 v210, v210, v169
	v_fmamk_f32 v210, v210, 0x3a000000, v241
	v_rsq_f32_e32 v194, v210
	ds_bpermute_b32 v222, v138, v144
	ds_bpermute_b32 v223, v138, v199
	ds_bpermute_b32 v218, v138, v209
	ds_bpermute_b32 v168, v138, v146
	s_waitcnt lgkmcnt(3)
	v_add_f32_e32 v144, v144, v222
	s_waitcnt lgkmcnt(2)
	v_add_f32_e32 v199, v199, v223
	s_waitcnt lgkmcnt(1)
	v_add_f32_e32 v209, v209, v218
	s_waitcnt lgkmcnt(0)
	v_add_f32_e32 v146, v146, v168
	ds_bpermute_b32 v145, v128, v144
	ds_bpermute_b32 v211, v128, v199
	ds_bpermute_b32 v213, v128, v209
	ds_bpermute_b32 v147, v128, v146
	s_waitcnt lgkmcnt(0)
	v_add_f32_e32 v210, v142, v143
	v_add_f32_e32 v214, v214, v215
	v_add_f32_e32 v218, v219, v225
	v_add_f32_e32 v198, v144, v145
	v_add_f32_e32 v202, v199, v211
	v_add_f32_e32 v204, v209, v213
	v_add_f32_e32 v196, v146, v147
	v_fmamk_f32 v210, v210, 0x3a000000, v241
	v_fmamk_f32 v214, v214, 0x3a000000, v241
	v_fmamk_f32 v218, v218, 0x3a000000, v241
	v_fmamk_f32 v198, v198, 0x3a000000, v241
	v_fmamk_f32 v202, v202, 0x3a000000, v241
	v_fmamk_f32 v204, v204, 0x3a000000, v241
	v_fmamk_f32 v196, v196, 0x3a000000, v241
	v_rsq_f32_e32 v210, v210
	v_rsq_f32_e32 v214, v214
	v_rsq_f32_e32 v218, v218
	v_rsq_f32_e32 v198, v198
	v_rsq_f32_e32 v202, v202
	v_rsq_f32_e32 v204, v204
	v_rsq_f32_e32 v196, v196
	v_writelane_b32 v255, s10, 40
	ds_write_b32 v235, v194 offset:192
	ds_write_b32 v235, v210
	ds_write_b32 v235, v214 offset:64
	ds_write_b32 v235, v218 offset:128
	ds_write_b32 v235, v198 offset:512
	ds_write_b32 v235, v202 offset:576
	ds_write_b32 v235, v204 offset:640
	ds_write_b32 v235, v196 offset:704
	s_branch .Lrs_done
; #define PG8_LAS __attribute__((address_space(3)))
;     __device__ __forceinline__ void operator()(const f32x4 (&acc)[2][2][4][2], const Unit& u, int wr, int wc, int fr, int fq) const {
;     ...
;             for (int m = 0; m < 4; ++m) rs[ai][m] = rs_from_partials(SS, row0 + ai * HALF + m * 16, fq);
; #pragma unroll
;         for (int ai = 0; ai < 2; ++ai) {
;             const int gi = ai * 2 + wr;
;             if (fr >= 14) {
;                 const int r = fr - 14;
; #pragma unroll
;                 for (int bj = 0; bj < 2; ++bj)
; #pragma unroll
;                     for (int n = 0; n < 2; ++n) { const f32x4 v = acc[ai][bj][3][n] * rs[ai][3];
;                         *(PG8_LAS f32x4*)(xch + ((((gi * 2 + r) * 2 + bj) * 128) + cidx + 4 * n) * 4) = v;
;                         if (gi == 3) *(f32x4*)(RAWB + ((size_t)u.pm * 4 + 2 + r) * 11264 + bj * 5632 + u.pn * 128 + cidx + 4 * n) = v; }
.Lrs_cached:
	ds_read_b32 v210, v235
	ds_read_b32 v214, v235 offset:64
	ds_read_b32 v218, v235 offset:128
	ds_read_b32 v194, v235 offset:192
	ds_read_b32 v198, v235 offset:512
	ds_read_b32 v202, v235 offset:576
	ds_read_b32 v204, v235 offset:640
	ds_read_b32 v196, v235 offset:704
.Lrs_done:
	s_waitcnt lgkmcnt(0)
	v_lshl_add_u64 v[130:131], v[182:183], 0, s[48:49]
	v_mad_u64_u32 v[138:139], s[10:11], v130, s54, 0
	s_lshl_b32 s10, s8, 7
	v_mad_i32_i24 v139, v131, s54, v139
	s_ashr_i32 s11, s10, 31
	s_and_saveexec_b64 s[8:9], s[4:5]
	s_movk_i32 s38, 0xfec0
	s_cbranch_execz .LBB0_1897
	v_mov_b32_e32 v140, v194
	v_mov_b32_e32 v141, v194
	v_pk_mul_f32 v[136:137], v[102:103], v[194:195] op_sel_hi:[1,0]
	v_pk_mul_f32 v[134:135], v[100:101], v[194:195] op_sel_hi:[1,0]
	s_mov_b64 s[74:75], -1
	s_and_b64 vcc, exec, s[20:21]
	v_pk_mul_f32 v[130:131], v[36:37], v[140:141]
	ds_write_b128 v252, v[134:137]
	s_cbranch_vccz .LBB0_1891
	v_mov_b32_e32 v195, v194
	v_pk_mul_f32 v[132:133], v[38:39], v[194:195]
	s_mov_b64 s[74:75], 0

; #define PG8_LAS __attribute__((address_space(3)))
;     __device__ __forceinline__ void operator()(const f32x4 (&acc)[2][2][4][2], const Unit& u, int wr, int wc, int fr, int fq) const {
;     ...
;             if (fr >= 14) {
;                 const int r = fr - 14;
; #pragma unroll
;                 for (int bj = 0; bj < 2; ++bj)
; #pragma unroll
;                     for (int n = 0; n < 2; ++n) { const f32x4 v = acc[ai][bj][3][n] * rs[ai][3];
;                         *(PG8_LAS f32x4*)(xch + ((((gi * 2 + r) * 2 + bj) * 128) + cidx + 4 * n) * 4) = v;
;                         if (gi == 3) *(f32x4*)(RAWB + ((size_t)u.pm * 4 + 2 + r) * 11264 + bj * 5632 + u.pn * 128 + cidx + 4 * n) = v; }
;             }
;             if (gi == 0 && fr < 2) {
; #pragma unroll
;                 for (int bj = 0; bj < 2; ++bj)
; #pragma unroll
;                     for (int n = 0; n < 2; ++n) *(f32x4*)(RAWB + ((size_t)u.pm * 4 + fr) * 11264 + bj * 5632 + u.pn * 128 + cidx + 4 * n) = acc[ai][bj][0][n] * rs[ai][0];
;             }
.LBB0_1897:
	s_or_b64 exec, exec, s[8:9]
	v_lshl_add_u64 v[130:131], s[48:49], 0, v[178:179]
	v_mad_u64_u32 v[132:133], s[8:9], v130, s54, 0
	v_mad_i32_i24 v133, v131, s54, v133
	v_lshl_add_u64 v[130:131], s[16:17], 0, v[132:133]
	v_lshl_add_u64 v[140:141], s[10:11], 2, v[130:131]
	v_lshlrev_b32_e32 v128, 2, v180
	s_and_saveexec_b64 s[8:9], s[22:23]
	s_cbranch_execz .LBB0_1899
	v_pk_mul_f32 v[132:133], v[126:127], v[210:211] op_sel_hi:[1,0]
	v_pk_mul_f32 v[130:131], v[124:125], v[210:211] op_sel_hi:[1,0]
	v_lshl_add_u64 v[134:135], v[140:141], 0, v[128:129]
	global_store_dwordx4 v[134:135], v[130:133], off
	s_nop 1
	v_pk_mul_f32 v[132:133], v[62:63], v[210:211] op_sel_hi:[1,0]
	v_pk_mul_f32 v[130:131], v[60:61], v[210:211] op_sel_hi:[1,0]
	global_store_dwordx4 v[134:135], v[130:133], off offset:16
	v_add_co_u32_e32 v134, vcc, 0x5000, v134
	s_nop 0
	v_pk_mul_f32 v[132:133], v[122:123], v[210:211] op_sel_hi:[1,0]
	v_pk_mul_f32 v[130:131], v[120:121], v[210:211] op_sel_hi:[1,0]
	v_addc_co_u32_e32 v135, vcc, 0, v135, vcc
	global_store_dwordx4 v[134:135], v[130:133], off offset:2048
	s_nop 1
	v_pk_mul_f32 v[132:133], v[58:59], v[210:211] op_sel_hi:[1,0]
	v_pk_mul_f32 v[130:131], v[56:57], v[210:211] op_sel_hi:[1,0]
	global_store_dwordx4 v[134:135], v[130:133], off offset:2064
.LBB0_1899:
	s_or_b64 exec, exec, s[8:9]
	s_waitcnt lgkmcnt(0)
	s_and_saveexec_b64 s[8:9], s[4:5]
	s_cbranch_execz .LBB0_1908
	v_mov_b32_e32 v142, v196
	v_mov_b32_e32 v143, v196
	v_pk_mul_f32 v[136:137], v[70:71], v[196:197] op_sel_hi:[1,0]
	v_pk_mul_f32 v[134:135], v[68:69], v[196:197] op_sel_hi:[1,0]
	s_mov_b64 s[48:49], -1
	s_and_b64 vcc, exec, s[24:25]
	v_pk_mul_f32 v[130:131], v[4:5], v[142:143]
	ds_write_b128 v253, v[134:137]
	s_cbranch_vccz .LBB0_1902
	v_mov_b32_e32 v197, v196
	v_pk_mul_f32 v[132:133], v[6:7], v[196:197]
	s_mov_b64 s[48:49], 0

;     __device__ __forceinline__ void operator()(const f32x4 (&acc)[2][2][4][2], const Unit& u, int wr, int wc, int fr, int fq) const {
;     ...
;             if (gi == 0 && fr < 2) {
; #pragma unroll
;                 for (int bj = 0; bj < 2; ++bj)
; #pragma unroll
;                     for (int n = 0; n < 2; ++n) *(f32x4*)(RAWB + ((size_t)u.pm * 4 + fr) * 11264 + bj * 5632 + u.pn * 128 + cidx + 4 * n) = acc[ai][bj][0][n] * rs[ai][0];
;             }
;         }
;         asm volatile("s_waitcnt lgkmcnt(0)" ::: "memory"); __builtin_amdgcn_s_barrier(); asm volatile("" ::: "memory");
; #pragma unroll
;         for (int n = 0; n < 2; ++n) {
;             f32x4 w[2][3];
; #pragma unroll
;             for (int bj = 0; bj < 2; ++bj)
; #pragma unroll
;                 for (int j = 0; j < 3; ++j) w[bj][j] = *(const f32x4*)(cw + j * 11264 + bj * 5632 + u.pn * 128 + cidx + 4 * n);
.LBB0_1908:
	s_or_b64 exec, exec, s[8:9]
	s_nop 0
	s_and_saveexec_b64 s[8:9], s[26:27]
	s_cbranch_execz .LBB0_1910
	v_pk_mul_f32 v[132:133], v[94:95], v[198:199] op_sel_hi:[1,0]
	v_pk_mul_f32 v[130:131], v[92:93], v[198:199] op_sel_hi:[1,0]
	v_lshl_add_u64 v[134:135], v[140:141], 0, v[128:129]
	global_store_dwordx4 v[134:135], v[130:133], off
	s_nop 1
	v_pk_mul_f32 v[132:133], v[30:31], v[198:199] op_sel_hi:[1,0]
	v_pk_mul_f32 v[130:131], v[28:29], v[198:199] op_sel_hi:[1,0]
	global_store_dwordx4 v[134:135], v[130:133], off offset:16
	v_add_co_u32_e32 v134, vcc, 0x5000, v134
	s_nop 0
	v_pk_mul_f32 v[132:133], v[90:91], v[198:199] op_sel_hi:[1,0]
	v_pk_mul_f32 v[130:131], v[88:89], v[198:199] op_sel_hi:[1,0]
	v_addc_co_u32_e32 v135, vcc, 0, v135, vcc
	global_store_dwordx4 v[134:135], v[130:133], off offset:2048
	s_nop 1
	v_pk_mul_f32 v[132:133], v[26:27], v[198:199] op_sel_hi:[1,0]
	v_pk_mul_f32 v[130:131], v[24:25], v[198:199] op_sel_hi:[1,0]
	global_store_dwordx4 v[134:135], v[130:133], off offset:2064
.LBB0_1910:
	s_or_b64 exec, exec, s[8:9]
	v_lshl_add_u64 v[222:223], s[10:11], 2, v[186:187]
	s_waitcnt lgkmcnt(0)
	s_barrier
	s_mov_b32 s9, 0
	global_load_dwordx4 v[130:133], v[222:223], off
	s_mov_b32 s8, 0xb000
	v_lshl_add_u64 v[234:235], v[222:223], 0, s[8:9]
	global_load_dwordx4 v[134:137], v[234:235], off
	s_mov_b32 s8, 0x16000
	v_lshl_add_u64 v[234:235], v[222:223], 0, s[8:9]
	global_load_dwordx4 v[138:141], v[234:235], off
	s_mov_b32 s8, 0x5800
	v_lshl_add_u64 v[234:235], v[222:223], 0, s[8:9]
	global_load_dwordx4 v[142:145], v[234:235], off
	s_mov_b32 s8, 0x10800
	v_lshl_add_u64 v[234:235], v[222:223], 0, s[8:9]
	global_load_dwordx4 v[146:149], v[234:235], off
	s_mov_b32 s8, 0x1b800
	v_lshl_add_u64 v[234:235], v[222:223], 0, s[8:9]
	global_load_dwordx4 v[150:153], v[234:235], off
	v_mov_b64_e32 v[234:235], s[14:15]
	v_mad_i64_i32 v[246:247], s[12:13], v228, s53, v[234:235]
	s_lshl_b64 s[74:75], s[10:11], 1
	v_lshl_add_u64 v[246:247], v[246:247], 0, s[74:75]
	v_lshlrev_b32_e32 v128, 1, v180
	v_lshl_add_u64 v[246:247], v[246:247], 0, v[128:129]
	s_and_b32 s8, s28, 0x800
	s_add_i32 s8, s8, s91
	s_addk_i32 s8, 0xf800
	v_add_u32_e32 v195, s8, v184
	v_cmp_eq_u32_e32 vcc, 14, v178
	v_add_u32_e32 v197, 0x400, v195
	v_cndmask_b32_e32 v197, v197, v195, vcc
	s_cmp_eq_u32 s28, 0
	s_cbranch_scc1 .Lupc_zero_b0
	ds_read_b128 v[154:157], v197
	ds_read_b128 v[158:161], v197 offset:512
	s_branch .Lupc_go_b0
